# mix part-2: short 4th round of items moved to less loaded half-workgroups (24..47)
# speedup vs baseline: 1.0832x; 1.0044x over previous
; DI int otid() { int t = threadIdx.x; asm volatile("" : "+v"(t)); return t; }
; DI void phase_mix(KP p, int l, char* lds) {
;     ...
;   const int xcd = blockIdx.x & 7, lb = 2 * (blockIdx.x >> 3) + __builtin_amdgcn_readfirstlane(otid() >> 8), nlb = 2 * (gridDim.x >> 3);
;   const int nDL = 64, nA = 0, nB = 0, nDC = upd ? 8 : 0, nAc = 0, nBc = 0, nCM = 72, nFN = upd ? 72 : 64;
;   const int e0 = nDL, e1 = e0 + nA, e2 = e1 + nB, e3 = e2 + nDC, e4 = e3 + nAc, e5 = e4 + nBc, e6 = e5 + nCM, e7 = e6 + nFN;
;   unsigned* cnt = (unsigned*)(ws + WS_CNT) + l * 288;
;   const bf16_t* wf = (const bf16_t*)(ws + WS_WF) + (size_t)l * 256 * 256;
;   {
;     const int lbw = blockIdx.x >> 3, nlbw = gridDim.x >> 3;
;     const int nW = upd ? 144 : 128;
;     for (int it = lbw; it < nW; it += nlbw) {
;       const bool isA = (it < 64) || (it >= 128 && it < 136);
;       int b, hd, q0, k0, nk;
;       if (it < 128) { const int i2 = it & 63; b = 2 * xcd + (i2 >> 5); hd = (i2 >> 3) & 3; q0 = (i2 & 7) * 256; k0 = 0; nk = T; }
;       else { const int i2 = (it - 128) & 7; b = 2 * xcd + (i2 >> 2); hd = i2 & 3; q0 = SEQ; k0 = SEQ; nk = CL; }
;       const size_t r0 = (size_t)b * T + q0; const size_t bh = (size_t)b * 4 + hd, bk = (size_t)b * 2 + (hd >> 1);
;       if (isA) {
;         if (sbA <= 30.f) attn_item8<96, true>(QA + (bh * T + q0) * 96, KA + (bh * T + k0) * 96, VAT + bh * 64 * T + k0, nk, lds, P + r0 * NIN + O_GA + 64 * hd, Y + r0 * 1024 + 64 * hd, sbA);
;         else attn_item8<96, false>(QA + (bh * T + q0) * 96, KA + (bh * T + k0) * 96, VAT + bh * 64 * T + k0, nk, lds, P + r0 * NIN + O_GA + 64 * hd, Y + r0 * 1024 + 64 * hd, 0.f);
;       } else {
;         if (sbB <= 30.f) attn_item8<64, true>(QB + (bh * T + q0) * 64, KB + (bk * T + k0) * 64, VBT + bk * 64 * T + k0, nk, lds, P + r0 * NIN + O_GB + 64 * hd, Y + r0 * 1024 + 256 + 64 * hd, sbB);
;         else attn_item8<64, false>(QB + (bh * T + q0) * 64, KB + (bk * T + k0) * 64, VBT + bk * 64 * T + k0, nk, lds, P + r0 * NIN + O_GB + 64 * hd, Y + r0 * 1024 + 256 + 64 * hd, 0.f);
;       }
;     }
;     __syncthreads();
;   }
;   const int tid0 = otid() & 255;
;   for (int it = lb; it < e7; it += nlb) {
.LBB0_123:
	v_readlane_b32 s19, v255, 37
	s_ashr_i32 s2, s19, 8
	v_readlane_b32 s4, v254, 40
	s_add_i32 s46, s2, s4
	s_mov_b32 s101, s46
	v_readlane_b32 s4, v255, 35
	v_readlane_b32 s5, v255, 36
	s_and_b64 s[4:5], s[4:5], exec
	s_cselect_b32 s47, 64, 0x48
	s_add_i32 s45, s47, 0x48
	s_add_i32 s14, s45, s47
	v_mov_b32_e32 v0, v196
	s_cmp_ge_i32 s46, s14
	s_waitcnt lgkmcnt(0)
	s_barrier
	s_cbranch_scc1 .LBB0_180
	v_readlane_b32 s34, v255, 33
	v_readlane_b32 s35, v255, 34
	s_add_u32 s2, s34, 0x14f75100
	v_writelane_b32 v255, s2, 38
	s_addc_u32 s2, s35, 0
	v_writelane_b32 v255, s2, 39
	s_add_u32 s2, s34, 0x1075100
	v_writelane_b32 v255, s2, 47
	s_addc_u32 s2, s35, 0
	v_writelane_b32 v255, s2, 48
	s_add_u32 s2, s34, 0x1875100
	v_writelane_b32 v255, s2, 49
	s_addc_u32 s2, s35, 0
	v_writelane_b32 v255, s2, 50
	s_add_u32 s2, s34, 0x1cd75100
	v_writelane_b32 v255, s2, 51
	s_addc_u32 s2, s35, 0
	v_writelane_b32 v255, s2, 53
	v_cmp_eq_u32_sdwa s[64:65], v0, v1 src0_sel:BYTE_0 src1_sel:DWORD
	v_readlane_b32 s20, v255, 26
	v_readlane_b32 s21, v255, 27
	s_ashr_i32 s21, s20, 31
	s_lshl_b64 s[4:5], s[20:21], 17
	s_add_u32 s2, s34, s4
	s_addc_u32 s18, s35, s5
	s_add_u32 s4, s2, 0x1031100
	v_writelane_b32 v255, s4, 55
	s_addc_u32 s4, s18, 0
	v_writelane_b32 v255, s4, 56
	s_mul_i32 s4, s20, 0x120
	s_ashr_i32 s5, s4, 31
	s_lshl_b64 s[4:5], s[4:5], 2
	s_add_u32 s4, s34, s4
	s_addc_u32 s5, s35, s5
	s_add_u32 s4, s4, 0x1ef88700
	v_writelane_b32 v255, s4, 43
	s_addc_u32 s4, s5, 0
	v_writelane_b32 v255, s4, 44
	s_add_u32 s2, s2, 0xbf1100
	v_writelane_b32 v255, s2, 40
	s_addc_u32 s2, s18, 0
	v_writelane_b32 v255, s2, 41
	s_mov_b32 s2, s20
	v_readlane_b32 s4, v255, 35
	v_readlane_b32 s5, v255, 36
	s_and_b64 s[4:5], s[4:5], exec
	v_writelane_b32 v255, s2, 26
	s_cselect_b32 s44, 16, 18
	s_lshl_b64 s[4:5], s[20:21], 11
	v_writelane_b32 v255, s3, 27
	v_writelane_b32 v255, s4, 57
	s_bfe_u32 s2, s19, 0x10008
	v_cvt_f32_ubyte0_e32 v0, s44
	v_writelane_b32 v255, s5, 58
	s_lshl_b32 s4, s2, 17
	s_add_u32 s4, s34, s4
	v_rcp_iflag_f32_e32 v0, v0
	s_addc_u32 s5, s35, 0
	s_add_u32 s4, s4, 0x14b75100
	v_writelane_b32 v255, s4, 37
	s_addc_u32 s4, s5, 0
	v_writelane_b32 v255, s4, 59
	s_lshl_b32 s4, s2, 19
	v_mul_f32_e32 v0, 0x4f7ffffe, v0
	s_add_u32 s4, s34, s4
	v_cvt_u32_f32_e32 v0, v0
	s_addc_u32 s5, s35, 0
	s_add_u32 s4, s4, 0x13b75100
	v_writelane_b32 v255, s4, 60
	s_addc_u32 s4, s5, 0
	v_writelane_b32 v255, s4, 61
	s_sub_i32 s4, 0, s44
	v_readfirstlane_b32 s5, v0
	s_mul_i32 s4, s4, s5
	s_mul_hi_u32 s4, s5, s4
	s_add_i32 s4, s5, s4
	v_writelane_b32 v255, s4, 42
	s_add_u32 s4, s34, 0x18b5500
	v_writelane_b32 v255, s4, 62
	s_addc_u32 s4, s35, 0
	s_lshl_b32 s2, s2, 8
	v_writelane_b32 v255, s4, 63
	s_add_u32 s4, s34, s2
	s_addc_u32 s5, s35, 0
	v_writelane_b32 v255, s4, 45
	s_nop 1
	v_writelane_b32 v255, s5, 46
	s_branch .LBB0_127

; DI void phase_mix(KP p, int l, char* lds) {
;     ...
;   for (int it = lb; it < e7; it += nlb) {
.LBB0_126:
	v_readlane_b32 s2, v253, 4
	s_add_i32 s101, s101, s2
	s_mov_b32 s46, s101
	s_cmp_lg_u32 s2, 64
	s_cbranch_scc1 .Lperm_done
	s_cmp_ge_i32 s101, 0x100
	s_cbranch_scc1 .LBB0_180
	s_cmp_lt_i32 s101, 0xc0
	s_cbranch_scc1 .Lperm_done
	s_add_i32 s46, s101, 40
	s_and_b32 s46, s46, 63
	s_addk_i32 s46, 0xc0
.Lperm_done:
	s_cmp_ge_i32 s46, s14
	s_cbranch_scc1 .LBB0_180
